# P2 slices: a w_cq row's 16 chunk loads requested at once instead of 16 dependent HBM round trips (each also drained the previous store)
# baseline (speedup 1.0000x reference)
.LBB0_216:
	s_waitcnt vmcnt(0)
	v_mov_b64_e32 v[6:7], s[92:93]
	flat_load_dwordx2 v[2:3], v[6:7] offset:64 sc0 sc1
	s_waitcnt vmcnt(0)
	s_lshl_b32 s0, s25, 4
	s_lshl_b32 s1, s24, 1
	s_add_i32 s0, s0, s1
	s_ashr_i32 s1, s0, 31
	s_lshl_b64 s[4:5], s[0:1], 2
	s_lshl_b64 s[6:7], s[0:1], 14
	v_lshlrev_b64 v[8:9], 4, v[134:135]
	v_lshl_add_u64 v[12:13], v[134:135], 3, s[14:15]
	s_lshl_b32 s10, s24, 12
	s_and_b32 s10, s10, 0x1000
	s_waitcnt lgkmcnt(0)
	v_lshl_add_u64 v[2:3], v[2:3], 0, s[4:5]
	flat_load_dword v18, v[2:3]
	s_nop 0
	flat_load_dwordx2 v[2:3], v[6:7] offset:80 sc0 sc1
	s_waitcnt vmcnt(0) lgkmcnt(0)
	v_lshl_add_u64 v[2:3], v[2:3], 0, s[6:7]
	v_lshl_add_u64 v[10:11], v[2:3], 0, v[8:9]
	v_add_co_u32_e32 v212, vcc, 0x1000, v10
	s_nop 1
	v_addc_co_u32_e32 v213, vcc, 0, v11, vcc
	v_add_co_u32_e32 v228, vcc, 0x2000, v10
	s_nop 1
	v_addc_co_u32_e32 v229, vcc, 0, v11, vcc
	v_add_co_u32_e32 v244, vcc, 0x3000, v10
	s_nop 1
	v_addc_co_u32_e32 v245, vcc, 0, v11, vcc
	global_load_dwordx4 v[184:187], v[10:11], off nt
	global_load_dwordx4 v[188:191], v[10:11], off offset:1024 nt
	global_load_dwordx4 v[192:195], v[10:11], off offset:2048 nt
	global_load_dwordx4 v[196:199], v[10:11], off offset:3072 nt
	global_load_dwordx4 v[200:203], v[212:213], off nt
	global_load_dwordx4 v[204:207], v[212:213], off offset:1024 nt
	global_load_dwordx4 v[208:211], v[212:213], off offset:2048 nt
	global_load_dwordx4 v[212:215], v[212:213], off offset:3072 nt
	global_load_dwordx4 v[216:219], v[228:229], off nt
	global_load_dwordx4 v[220:223], v[228:229], off offset:1024 nt
	global_load_dwordx4 v[224:227], v[228:229], off offset:2048 nt
	global_load_dwordx4 v[228:231], v[228:229], off offset:3072 nt
	global_load_dwordx4 v[232:235], v[244:245], off nt
	global_load_dwordx4 v[236:239], v[244:245], off offset:1024 nt
	global_load_dwordx4 v[240:243], v[244:245], off offset:2048 nt
	global_load_dwordx4 v[244:247], v[244:245], off offset:3072 nt
	s_lshl_b64 s[6:7], s[0:1], 13
	v_lshl_add_u64 v[14:15], v[12:13], 0, s[6:7]
	s_movk_i32 s1, 0x1000
	v_add_co_u32_e32 v16, vcc, s1, v10
	s_movk_i32 s6, 0x2000
	s_nop 0
	v_addc_co_u32_e32 v17, vcc, 0, v11, vcc
	s_movk_i32 s7, 0x3000
	s_waitcnt vmcnt(0) lgkmcnt(0)
	v_mov_b32_e32 v2, v184
	v_mov_b32_e32 v3, v185
	v_mov_b32_e32 v4, v186
	v_mov_b32_e32 v5, v187
	v_mul_f32_e32 v2, v18, v2
	v_mul_f32_e32 v3, v18, v3
	v_mul_f32_e32 v4, v18, v4
	v_mul_f32_e32 v5, v18, v5
	v_cvt_pk_bf16_f32 v2, v2, v3
	v_cvt_pk_bf16_f32 v3, v4, v5
	global_store_dwordx2 v[14:15], v[2:3], off
	s_nop 1
	v_mov_b32_e32 v2, v188
	v_mov_b32_e32 v3, v189
	v_mov_b32_e32 v4, v190
	v_mov_b32_e32 v5, v191
	v_mul_f32_e32 v2, v18, v2
	v_mul_f32_e32 v3, v18, v3
	v_mul_f32_e32 v4, v18, v4
	v_mul_f32_e32 v5, v18, v5
	v_cvt_pk_bf16_f32 v2, v2, v3
	v_cvt_pk_bf16_f32 v3, v4, v5
	global_store_dwordx2 v[14:15], v[2:3], off offset:512
	s_nop 1
	v_mov_b32_e32 v2, v192
	v_mov_b32_e32 v3, v193
	v_mov_b32_e32 v4, v194
	v_mov_b32_e32 v5, v195
	v_mul_f32_e32 v2, v18, v2
	v_mul_f32_e32 v3, v18, v3
	v_mul_f32_e32 v4, v18, v4
	v_mul_f32_e32 v5, v18, v5
	v_cvt_pk_bf16_f32 v2, v2, v3
	v_cvt_pk_bf16_f32 v3, v4, v5
	global_store_dwordx2 v[14:15], v[2:3], off offset:1024
	s_nop 1
	v_mov_b32_e32 v2, v196
	v_mov_b32_e32 v3, v197
	v_mov_b32_e32 v4, v198
	v_mov_b32_e32 v5, v199
	v_mul_f32_e32 v2, v18, v2
	v_mul_f32_e32 v3, v18, v3
	v_mul_f32_e32 v4, v18, v4
	v_mul_f32_e32 v5, v18, v5
	v_cvt_pk_bf16_f32 v2, v2, v3
	v_cvt_pk_bf16_f32 v3, v4, v5
	global_store_dwordx2 v[14:15], v[2:3], off offset:1536
	s_nop 1
	v_mov_b32_e32 v2, v200
	v_mov_b32_e32 v3, v201
	v_mov_b32_e32 v4, v202
	v_mov_b32_e32 v5, v203
	v_mul_f32_e32 v2, v18, v2
	v_mul_f32_e32 v3, v18, v3
	v_mul_f32_e32 v4, v18, v4
	v_mul_f32_e32 v5, v18, v5
	v_cvt_pk_bf16_f32 v2, v2, v3
	v_cvt_pk_bf16_f32 v3, v4, v5
	global_store_dwordx2 v[14:15], v[2:3], off offset:2048
	s_nop 1
	v_mov_b32_e32 v2, v204
	v_mov_b32_e32 v3, v205
	v_mov_b32_e32 v4, v206
	v_mov_b32_e32 v5, v207
	v_mul_f32_e32 v2, v18, v2
	v_mul_f32_e32 v3, v18, v3
	v_mul_f32_e32 v4, v18, v4
	v_mul_f32_e32 v5, v18, v5
	v_cvt_pk_bf16_f32 v2, v2, v3
	v_cvt_pk_bf16_f32 v3, v4, v5
	global_store_dwordx2 v[14:15], v[2:3], off offset:2560
	s_nop 1
	v_mov_b32_e32 v2, v208
	v_mov_b32_e32 v3, v209
	v_mov_b32_e32 v4, v210
	v_mov_b32_e32 v5, v211
	v_mul_f32_e32 v2, v18, v2
	v_mul_f32_e32 v3, v18, v3
	v_mul_f32_e32 v4, v18, v4
	v_mul_f32_e32 v5, v18, v5
	v_cvt_pk_bf16_f32 v2, v2, v3
	v_cvt_pk_bf16_f32 v3, v4, v5
	global_store_dwordx2 v[14:15], v[2:3], off offset:3072
	s_nop 1
	v_mov_b32_e32 v2, v212
	v_mov_b32_e32 v3, v213
	v_mov_b32_e32 v4, v214
	v_mov_b32_e32 v5, v215
	v_add_co_u32_e32 v16, vcc, s6, v10
	v_mul_f32_e32 v2, v18, v2
	v_mul_f32_e32 v3, v18, v3
	v_addc_co_u32_e32 v17, vcc, 0, v11, vcc
	v_mul_f32_e32 v4, v18, v4
	v_mul_f32_e32 v5, v18, v5
	v_cvt_pk_bf16_f32 v2, v2, v3
	v_cvt_pk_bf16_f32 v3, v4, v5
	global_store_dwordx2 v[14:15], v[2:3], off offset:3584
	s_nop 1
	v_mov_b32_e32 v2, v216
	v_mov_b32_e32 v3, v217
	v_mov_b32_e32 v4, v218
	v_mov_b32_e32 v5, v219
	v_add_co_u32_e32 v14, vcc, s1, v14
	v_mul_f32_e32 v2, v18, v2
	v_addc_co_u32_e32 v15, vcc, 0, v15, vcc
	v_mul_f32_e32 v3, v18, v3
	v_mul_f32_e32 v4, v18, v4
	v_mul_f32_e32 v5, v18, v5
	v_cvt_pk_bf16_f32 v2, v2, v3
	v_cvt_pk_bf16_f32 v3, v4, v5
	global_store_dwordx2 v[14:15], v[2:3], off
	s_nop 1
	v_mov_b32_e32 v2, v220
	v_mov_b32_e32 v3, v221
	v_mov_b32_e32 v4, v222
	v_mov_b32_e32 v5, v223
	v_add_co_u32_e32 v10, vcc, s7, v10
	v_mul_f32_e32 v2, v18, v2
	v_mul_f32_e32 v3, v18, v3
	v_mul_f32_e32 v4, v18, v4
	v_mul_f32_e32 v5, v18, v5
	v_cvt_pk_bf16_f32 v2, v2, v3
	v_cvt_pk_bf16_f32 v3, v4, v5
	global_store_dwordx2 v[14:15], v[2:3], off offset:512
	s_nop 1
	v_mov_b32_e32 v2, v224
	v_mov_b32_e32 v3, v225
	v_mov_b32_e32 v4, v226
	v_mov_b32_e32 v5, v227
	v_addc_co_u32_e32 v11, vcc, 0, v11, vcc
	v_mul_f32_e32 v2, v18, v2
	v_mul_f32_e32 v3, v18, v3
	v_mul_f32_e32 v4, v18, v4
	v_mul_f32_e32 v5, v18, v5
	v_cvt_pk_bf16_f32 v2, v2, v3
	v_cvt_pk_bf16_f32 v3, v4, v5
	global_store_dwordx2 v[14:15], v[2:3], off offset:1024
	s_nop 1
	v_mov_b32_e32 v2, v228
	v_mov_b32_e32 v3, v229
	v_mov_b32_e32 v4, v230
	v_mov_b32_e32 v5, v231
	v_mul_f32_e32 v2, v18, v2
	v_mul_f32_e32 v3, v18, v3
	v_mul_f32_e32 v4, v18, v4
	v_mul_f32_e32 v5, v18, v5
	v_cvt_pk_bf16_f32 v2, v2, v3
	v_cvt_pk_bf16_f32 v3, v4, v5
	global_store_dwordx2 v[14:15], v[2:3], off offset:1536
	s_nop 1
	v_mov_b32_e32 v2, v232
	v_mov_b32_e32 v3, v233
	v_mov_b32_e32 v4, v234
	v_mov_b32_e32 v5, v235
	v_mul_f32_e32 v2, v18, v2
	v_mul_f32_e32 v3, v18, v3
	v_mul_f32_e32 v4, v18, v4
	v_mul_f32_e32 v5, v18, v5
	v_cvt_pk_bf16_f32 v2, v2, v3
	v_cvt_pk_bf16_f32 v3, v4, v5
	global_store_dwordx2 v[14:15], v[2:3], off offset:2048
	s_nop 1
	v_mov_b32_e32 v2, v236
	v_mov_b32_e32 v3, v237
	v_mov_b32_e32 v4, v238
	v_mov_b32_e32 v5, v239
	v_mul_f32_e32 v2, v18, v2
	v_mul_f32_e32 v3, v18, v3
	v_mul_f32_e32 v4, v18, v4
	v_mul_f32_e32 v5, v18, v5
	v_cvt_pk_bf16_f32 v2, v2, v3
	v_cvt_pk_bf16_f32 v3, v4, v5
	global_store_dwordx2 v[14:15], v[2:3], off offset:2560
	s_nop 1
	v_mov_b32_e32 v2, v240
	v_mov_b32_e32 v3, v241
	v_mov_b32_e32 v4, v242
	v_mov_b32_e32 v5, v243
	v_mul_f32_e32 v2, v18, v2
	v_mul_f32_e32 v3, v18, v3
	v_mul_f32_e32 v4, v18, v4
	v_mul_f32_e32 v5, v18, v5
	v_cvt_pk_bf16_f32 v2, v2, v3
	v_cvt_pk_bf16_f32 v3, v4, v5
	global_store_dwordx2 v[14:15], v[2:3], off offset:3072
	s_nop 1
	v_mov_b32_e32 v2, v244
	v_mov_b32_e32 v3, v245
	v_mov_b32_e32 v4, v246
	v_mov_b32_e32 v5, v247
	v_mul_f32_e32 v2, v18, v2
	v_mul_f32_e32 v3, v18, v3
	v_mul_f32_e32 v4, v18, v4
	v_mul_f32_e32 v5, v18, v5
	v_cvt_pk_bf16_f32 v2, v2, v3
	v_cvt_pk_bf16_f32 v3, v4, v5
	global_store_dwordx2 v[14:15], v[2:3], off offset:3584
	flat_load_dwordx2 v[2:3], v[6:7] offset:64 sc0 sc1
	s_waitcnt vmcnt(0) lgkmcnt(0)
	v_lshl_add_u64 v[2:3], v[2:3], 0, s[4:5]
	flat_load_dword v20, v[2:3] offset:4
	s_nop 0
	flat_load_dwordx2 v[2:3], v[6:7] offset:80 sc0 sc1
	s_waitcnt vmcnt(0)
	s_or_b32 s4, s0, 1
	s_ashr_i32 s5, s4, 31
	s_lshl_b64 s[8:9], s[4:5], 14
	s_lshl_b64 s[4:5], s[4:5], 13
	s_waitcnt lgkmcnt(0)
	v_lshl_add_u64 v[2:3], v[2:3], 0, s[8:9]
	v_lshl_add_u64 v[6:7], v[2:3], 0, v[8:9]
	v_add_co_u32_e32 v212, vcc, 0x1000, v6
	s_nop 1
	v_addc_co_u32_e32 v213, vcc, 0, v7, vcc
	v_add_co_u32_e32 v228, vcc, 0x2000, v6
	s_nop 1
	v_addc_co_u32_e32 v229, vcc, 0, v7, vcc
	v_add_co_u32_e32 v244, vcc, 0x3000, v6
	s_nop 1
	v_addc_co_u32_e32 v245, vcc, 0, v7, vcc
	global_load_dwordx4 v[184:187], v[6:7], off nt
	global_load_dwordx4 v[188:191], v[6:7], off offset:1024 nt
	global_load_dwordx4 v[192:195], v[6:7], off offset:2048 nt
	global_load_dwordx4 v[196:199], v[6:7], off offset:3072 nt
	global_load_dwordx4 v[200:203], v[212:213], off nt
	global_load_dwordx4 v[204:207], v[212:213], off offset:1024 nt
	global_load_dwordx4 v[208:211], v[212:213], off offset:2048 nt
	global_load_dwordx4 v[212:215], v[212:213], off offset:3072 nt
	global_load_dwordx4 v[216:219], v[228:229], off nt
	global_load_dwordx4 v[220:223], v[228:229], off offset:1024 nt
	global_load_dwordx4 v[224:227], v[228:229], off offset:2048 nt
	global_load_dwordx4 v[228:231], v[228:229], off offset:3072 nt
	global_load_dwordx4 v[232:235], v[244:245], off nt
	global_load_dwordx4 v[236:239], v[244:245], off offset:1024 nt
	global_load_dwordx4 v[240:243], v[244:245], off offset:2048 nt
	global_load_dwordx4 v[244:247], v[244:245], off offset:3072 nt
	v_lshl_add_u64 v[8:9], v[12:13], 0, s[4:5]
	v_add_co_u32_e32 v10, vcc, s1, v6
	s_add_i32 s4, s24, s57
	s_nop 0
	v_addc_co_u32_e32 v11, vcc, 0, v7, vcc
	s_lshl_b32 s4, s4, 3
	s_mov_b64 s[8:9], 0x26000100
	s_movk_i32 s5, 0xffe0
	s_waitcnt vmcnt(0) lgkmcnt(0)
	v_mov_b32_e32 v2, v184
	v_mov_b32_e32 v3, v185
	v_mov_b32_e32 v4, v186
	v_mov_b32_e32 v5, v187
	v_mul_f32_e32 v2, v20, v2
	v_mul_f32_e32 v3, v20, v3
	v_mul_f32_e32 v4, v20, v4
	v_mul_f32_e32 v5, v20, v5
	v_cvt_pk_bf16_f32 v2, v2, v3
	v_cvt_pk_bf16_f32 v3, v4, v5
	global_store_dwordx2 v[8:9], v[2:3], off
	s_nop 1
	v_mov_b32_e32 v2, v188
	v_mov_b32_e32 v3, v189
	v_mov_b32_e32 v4, v190
	v_mov_b32_e32 v5, v191
	v_mul_f32_e32 v2, v20, v2
	v_mul_f32_e32 v3, v20, v3
	v_mul_f32_e32 v4, v20, v4
	v_mul_f32_e32 v5, v20, v5
	v_cvt_pk_bf16_f32 v2, v2, v3
	v_cvt_pk_bf16_f32 v3, v4, v5
	global_store_dwordx2 v[8:9], v[2:3], off offset:512
	s_nop 1
	v_mov_b32_e32 v2, v192
	v_mov_b32_e32 v3, v193
	v_mov_b32_e32 v4, v194
	v_mov_b32_e32 v5, v195
	v_mul_f32_e32 v2, v20, v2
	v_mul_f32_e32 v3, v20, v3
	v_mul_f32_e32 v4, v20, v4
	v_mul_f32_e32 v5, v20, v5
	v_cvt_pk_bf16_f32 v2, v2, v3
	v_cvt_pk_bf16_f32 v3, v4, v5
	global_store_dwordx2 v[8:9], v[2:3], off offset:1024
	s_nop 1
	v_mov_b32_e32 v2, v196
	v_mov_b32_e32 v3, v197
	v_mov_b32_e32 v4, v198
	v_mov_b32_e32 v5, v199
	v_mul_f32_e32 v2, v20, v2
	v_mul_f32_e32 v3, v20, v3
	v_mul_f32_e32 v4, v20, v4
	v_mul_f32_e32 v5, v20, v5
	v_cvt_pk_bf16_f32 v2, v2, v3
	v_cvt_pk_bf16_f32 v3, v4, v5
	global_store_dwordx2 v[8:9], v[2:3], off offset:1536
	s_nop 1
	v_mov_b32_e32 v2, v200
	v_mov_b32_e32 v3, v201
	v_mov_b32_e32 v4, v202
	v_mov_b32_e32 v5, v203
	v_mul_f32_e32 v2, v20, v2
	v_mul_f32_e32 v3, v20, v3
	v_mul_f32_e32 v4, v20, v4
	v_mul_f32_e32 v5, v20, v5
	v_cvt_pk_bf16_f32 v2, v2, v3
	v_cvt_pk_bf16_f32 v3, v4, v5
	global_store_dwordx2 v[8:9], v[2:3], off offset:2048
	s_nop 1
	v_mov_b32_e32 v2, v204
	v_mov_b32_e32 v3, v205
	v_mov_b32_e32 v4, v206
	v_mov_b32_e32 v5, v207
	v_mul_f32_e32 v2, v20, v2
	v_mul_f32_e32 v3, v20, v3
	v_mul_f32_e32 v4, v20, v4
	v_mul_f32_e32 v5, v20, v5
	v_cvt_pk_bf16_f32 v2, v2, v3
	v_cvt_pk_bf16_f32 v3, v4, v5
	global_store_dwordx2 v[8:9], v[2:3], off offset:2560
	s_nop 1
	v_mov_b32_e32 v2, v208
	v_mov_b32_e32 v3, v209
	v_mov_b32_e32 v4, v210
	v_mov_b32_e32 v5, v211
	v_mul_f32_e32 v2, v20, v2
	v_mul_f32_e32 v3, v20, v3
	v_mul_f32_e32 v4, v20, v4
	v_mul_f32_e32 v5, v20, v5
	v_cvt_pk_bf16_f32 v2, v2, v3
	v_cvt_pk_bf16_f32 v3, v4, v5
	global_store_dwordx2 v[8:9], v[2:3], off offset:3072
	s_nop 1
	v_mov_b32_e32 v2, v212
	v_mov_b32_e32 v3, v213
	v_mov_b32_e32 v4, v214
	v_mov_b32_e32 v5, v215
	v_add_co_u32_e32 v10, vcc, s6, v6
	v_mul_f32_e32 v2, v20, v2
	v_mul_f32_e32 v3, v20, v3
	v_addc_co_u32_e32 v11, vcc, 0, v7, vcc
	v_mul_f32_e32 v4, v20, v4
	v_mul_f32_e32 v5, v20, v5
	v_cvt_pk_bf16_f32 v2, v2, v3
	v_cvt_pk_bf16_f32 v3, v4, v5
	global_store_dwordx2 v[8:9], v[2:3], off offset:3584
	s_nop 1
	v_mov_b32_e32 v2, v216
	v_mov_b32_e32 v3, v217
	v_mov_b32_e32 v4, v218
	v_mov_b32_e32 v5, v219
	v_add_co_u32_e32 v16, vcc, s1, v8
	v_lshlrev_b32_e32 v8, 3, v150
	s_nop 0
	v_addc_co_u32_e32 v17, vcc, 0, v9, vcc
	v_add_co_u32_e32 v6, vcc, s7, v6
	v_ashrrev_i32_e32 v9, 31, v8
	s_nop 0
	v_addc_co_u32_e32 v7, vcc, 0, v7, vcc
	v_lshlrev_b64 v[18:19], 1, v[8:9]
	s_mov_b64 s[6:7], 0x4e500100
	s_mov_b64 s[0:1], 0x200
	v_mul_f32_e32 v2, v20, v2
	v_mul_f32_e32 v3, v20, v3
	v_mul_f32_e32 v4, v20, v4
	v_mul_f32_e32 v5, v20, v5
	v_cvt_pk_bf16_f32 v2, v2, v3
	v_cvt_pk_bf16_f32 v3, v4, v5
	global_store_dwordx2 v[16:17], v[2:3], off
	s_nop 1
	v_mov_b32_e32 v2, v220
	v_mov_b32_e32 v3, v221
	v_mov_b32_e32 v4, v222
	v_mov_b32_e32 v5, v223
	v_mul_f32_e32 v2, v20, v2
	v_mul_f32_e32 v3, v20, v3
	v_mul_f32_e32 v4, v20, v4
	v_mul_f32_e32 v5, v20, v5
	v_cvt_pk_bf16_f32 v2, v2, v3
	v_cvt_pk_bf16_f32 v3, v4, v5
	global_store_dwordx2 v[16:17], v[2:3], off offset:512
	s_nop 1
	v_mov_b32_e32 v2, v224
	v_mov_b32_e32 v3, v225
	v_mov_b32_e32 v4, v226
	v_mov_b32_e32 v5, v227
	v_mul_f32_e32 v2, v20, v2
	v_mul_f32_e32 v3, v20, v3
	v_mul_f32_e32 v4, v20, v4
	v_mul_f32_e32 v5, v20, v5
	v_cvt_pk_bf16_f32 v2, v2, v3
	v_cvt_pk_bf16_f32 v3, v4, v5
	global_store_dwordx2 v[16:17], v[2:3], off offset:1024
	s_nop 1
	v_mov_b32_e32 v2, v228
	v_mov_b32_e32 v3, v229
	v_mov_b32_e32 v4, v230
	v_mov_b32_e32 v5, v231
	v_bfi_b32 v10, -16, s4, v134
	v_ashrrev_i32_e32 v11, 31, v10
	v_lshlrev_b64 v[10:11], 13, v[10:11]
	v_or_b32_e32 v10, s10, v10
	v_lshl_add_u64 v[10:11], v[10:11], 0, v[18:19]
	v_lshl_add_u64 v[10:11], s[78:79], 0, v[10:11]
	v_lshl_add_u64 v[10:11], v[10:11], 0, s[8:9]
	v_mul_f32_e32 v2, v20, v2
	v_mul_f32_e32 v3, v20, v3
	v_mul_f32_e32 v4, v20, v4
	v_mul_f32_e32 v5, v20, v5
	v_cvt_pk_bf16_f32 v2, v2, v3
	v_cvt_pk_bf16_f32 v3, v4, v5
	global_store_dwordx2 v[16:17], v[2:3], off offset:1536
	s_nop 1
	v_mov_b32_e32 v2, v232
	v_mov_b32_e32 v3, v233
	v_mov_b32_e32 v4, v234
	v_mov_b32_e32 v5, v235
	v_mul_f32_e32 v2, v20, v2
	v_mul_f32_e32 v3, v20, v3
	v_mul_f32_e32 v4, v20, v4
	v_mul_f32_e32 v5, v20, v5
	v_cvt_pk_bf16_f32 v2, v2, v3
	v_cvt_pk_bf16_f32 v3, v4, v5
	global_store_dwordx2 v[16:17], v[2:3], off offset:2048
	s_nop 1
	v_mov_b32_e32 v2, v236
	v_mov_b32_e32 v3, v237
	v_mov_b32_e32 v4, v238
	v_mov_b32_e32 v5, v239
	v_mul_f32_e32 v2, v20, v2
	v_mul_f32_e32 v3, v20, v3
	v_mul_f32_e32 v4, v20, v4
	v_mul_f32_e32 v5, v20, v5
	v_cvt_pk_bf16_f32 v2, v2, v3
	v_cvt_pk_bf16_f32 v3, v4, v5
	global_store_dwordx2 v[16:17], v[2:3], off offset:2560
	s_nop 1
	v_mov_b32_e32 v2, v240
	v_mov_b32_e32 v3, v241
	v_mov_b32_e32 v4, v242
	v_mov_b32_e32 v5, v243
	v_mul_f32_e32 v2, v20, v2
	v_mul_f32_e32 v3, v20, v3
	v_mul_f32_e32 v4, v20, v4
	v_mul_f32_e32 v5, v20, v5
	v_cvt_pk_bf16_f32 v2, v2, v3
	v_cvt_pk_bf16_f32 v3, v4, v5
	global_store_dwordx2 v[16:17], v[2:3], off offset:3072
	s_nop 1
	v_mov_b32_e32 v12, v244
	v_mov_b32_e32 v13, v245
	v_mov_b32_e32 v14, v246
	v_mov_b32_e32 v15, v247
	v_and_b32_e32 v6, 15, v134
	v_mov_b32_e32 v3, 0
	v_lshl_or_b32 v2, v6, 13, s10
	v_lshl_add_u64 v[8:9], v[2:3], 0, v[18:19]
	v_lshl_add_u64 v[8:9], s[78:79], 0, v[8:9]
	v_mov_b32_e32 v4, v3
	v_mov_b32_e32 v2, v3
	v_lshl_add_u64 v[8:9], v[8:9], 0, s[6:7]
	v_mul_f32_e32 v5, v20, v12
	v_mul_f32_e32 v7, v20, v13
	v_mul_f32_e32 v13, v20, v14
	v_cvt_pk_bf16_f32 v12, v5, v7
	v_mov_b32_e32 v5, v3
	v_mul_f32_e32 v14, v20, v15
	v_cvt_pk_bf16_f32 v13, v13, v14
	global_store_dwordx2 v[16:17], v[12:13], off offset:3584

.LBB0_328:
	s_waitcnt vmcnt(0)
	v_mov_b64_e32 v[6:7], s[92:93]
	flat_load_dwordx2 v[2:3], v[6:7] offset:64 sc0 sc1
	s_waitcnt vmcnt(0)
	s_lshl_b32 s0, s27, 4
	s_lshl_b32 s1, s26, 1
	s_add_i32 s0, s0, s1
	s_ashr_i32 s1, s0, 31
	s_lshl_b64 s[6:7], s[0:1], 2
	s_lshl_b64 s[8:9], s[0:1], 14
	v_lshlrev_b64 v[8:9], 4, v[134:135]
	v_lshl_add_u64 v[12:13], v[134:135], 3, s[14:15]
	s_lshl_b32 s12, s26, 12
	s_and_b32 s12, s12, 0x1000
	s_waitcnt lgkmcnt(0)
	v_lshl_add_u64 v[2:3], v[2:3], 0, s[6:7]
	flat_load_dword v18, v[2:3]
	s_nop 0
	flat_load_dwordx2 v[2:3], v[6:7] offset:80 sc0 sc1
	s_waitcnt vmcnt(0) lgkmcnt(0)
	v_lshl_add_u64 v[2:3], v[2:3], 0, s[8:9]
	v_lshl_add_u64 v[10:11], v[2:3], 0, v[8:9]
	v_add_co_u32_e32 v212, vcc, 0x1000, v10
	s_nop 1
	v_addc_co_u32_e32 v213, vcc, 0, v11, vcc
	v_add_co_u32_e32 v228, vcc, 0x2000, v10
	s_nop 1
	v_addc_co_u32_e32 v229, vcc, 0, v11, vcc
	v_add_co_u32_e32 v244, vcc, 0x3000, v10
	s_nop 1
	v_addc_co_u32_e32 v245, vcc, 0, v11, vcc
	global_load_dwordx4 v[184:187], v[10:11], off nt
	global_load_dwordx4 v[188:191], v[10:11], off offset:1024 nt
	global_load_dwordx4 v[192:195], v[10:11], off offset:2048 nt
	global_load_dwordx4 v[196:199], v[10:11], off offset:3072 nt
	global_load_dwordx4 v[200:203], v[212:213], off nt
	global_load_dwordx4 v[204:207], v[212:213], off offset:1024 nt
	global_load_dwordx4 v[208:211], v[212:213], off offset:2048 nt
	global_load_dwordx4 v[212:215], v[212:213], off offset:3072 nt
	global_load_dwordx4 v[216:219], v[228:229], off nt
	global_load_dwordx4 v[220:223], v[228:229], off offset:1024 nt
	global_load_dwordx4 v[224:227], v[228:229], off offset:2048 nt
	global_load_dwordx4 v[228:231], v[228:229], off offset:3072 nt
	global_load_dwordx4 v[232:235], v[244:245], off nt
	global_load_dwordx4 v[236:239], v[244:245], off offset:1024 nt
	global_load_dwordx4 v[240:243], v[244:245], off offset:2048 nt
	global_load_dwordx4 v[244:247], v[244:245], off offset:3072 nt
	s_lshl_b64 s[8:9], s[0:1], 13
	v_lshl_add_u64 v[14:15], v[12:13], 0, s[8:9]
	s_movk_i32 s1, 0x1000
	v_add_co_u32_e32 v16, vcc, s1, v10
	s_movk_i32 s8, 0x2000
	s_nop 0
	v_addc_co_u32_e32 v17, vcc, 0, v11, vcc
	s_movk_i32 s9, 0x3000
	s_waitcnt vmcnt(0) lgkmcnt(0)
	v_mov_b32_e32 v2, v184
	v_mov_b32_e32 v3, v185
	v_mov_b32_e32 v4, v186
	v_mov_b32_e32 v5, v187
	v_mul_f32_e32 v2, v18, v2
	v_mul_f32_e32 v3, v18, v3
	v_mul_f32_e32 v4, v18, v4
	v_mul_f32_e32 v5, v18, v5
	v_cvt_pk_bf16_f32 v2, v2, v3
	v_cvt_pk_bf16_f32 v3, v4, v5
	global_store_dwordx2 v[14:15], v[2:3], off
	s_nop 1
	v_mov_b32_e32 v2, v188
	v_mov_b32_e32 v3, v189
	v_mov_b32_e32 v4, v190
	v_mov_b32_e32 v5, v191
	v_mul_f32_e32 v2, v18, v2
	v_mul_f32_e32 v3, v18, v3
	v_mul_f32_e32 v4, v18, v4
	v_mul_f32_e32 v5, v18, v5
	v_cvt_pk_bf16_f32 v2, v2, v3
	v_cvt_pk_bf16_f32 v3, v4, v5
	global_store_dwordx2 v[14:15], v[2:3], off offset:512
	s_nop 1
	v_mov_b32_e32 v2, v192
	v_mov_b32_e32 v3, v193
	v_mov_b32_e32 v4, v194
	v_mov_b32_e32 v5, v195
	v_mul_f32_e32 v2, v18, v2
	v_mul_f32_e32 v3, v18, v3
	v_mul_f32_e32 v4, v18, v4
	v_mul_f32_e32 v5, v18, v5
	v_cvt_pk_bf16_f32 v2, v2, v3
	v_cvt_pk_bf16_f32 v3, v4, v5
	global_store_dwordx2 v[14:15], v[2:3], off offset:1024
	s_nop 1
	v_mov_b32_e32 v2, v196
	v_mov_b32_e32 v3, v197
	v_mov_b32_e32 v4, v198
	v_mov_b32_e32 v5, v199
	v_mul_f32_e32 v2, v18, v2
	v_mul_f32_e32 v3, v18, v3
	v_mul_f32_e32 v4, v18, v4
	v_mul_f32_e32 v5, v18, v5
	v_cvt_pk_bf16_f32 v2, v2, v3
	v_cvt_pk_bf16_f32 v3, v4, v5
	global_store_dwordx2 v[14:15], v[2:3], off offset:1536
	s_nop 1
	v_mov_b32_e32 v2, v200
	v_mov_b32_e32 v3, v201
	v_mov_b32_e32 v4, v202
	v_mov_b32_e32 v5, v203
	v_mul_f32_e32 v2, v18, v2
	v_mul_f32_e32 v3, v18, v3
	v_mul_f32_e32 v4, v18, v4
	v_mul_f32_e32 v5, v18, v5
	v_cvt_pk_bf16_f32 v2, v2, v3
	v_cvt_pk_bf16_f32 v3, v4, v5
	global_store_dwordx2 v[14:15], v[2:3], off offset:2048
	s_nop 1
	v_mov_b32_e32 v2, v204
	v_mov_b32_e32 v3, v205
	v_mov_b32_e32 v4, v206
	v_mov_b32_e32 v5, v207
	v_mul_f32_e32 v2, v18, v2
	v_mul_f32_e32 v3, v18, v3
	v_mul_f32_e32 v4, v18, v4
	v_mul_f32_e32 v5, v18, v5
	v_cvt_pk_bf16_f32 v2, v2, v3
	v_cvt_pk_bf16_f32 v3, v4, v5
	global_store_dwordx2 v[14:15], v[2:3], off offset:2560
	s_nop 1
	v_mov_b32_e32 v2, v208
	v_mov_b32_e32 v3, v209
	v_mov_b32_e32 v4, v210
	v_mov_b32_e32 v5, v211
	v_mul_f32_e32 v2, v18, v2
	v_mul_f32_e32 v3, v18, v3
	v_mul_f32_e32 v4, v18, v4
	v_mul_f32_e32 v5, v18, v5
	v_cvt_pk_bf16_f32 v2, v2, v3
	v_cvt_pk_bf16_f32 v3, v4, v5
	global_store_dwordx2 v[14:15], v[2:3], off offset:3072
	s_nop 1
	v_mov_b32_e32 v2, v212
	v_mov_b32_e32 v3, v213
	v_mov_b32_e32 v4, v214
	v_mov_b32_e32 v5, v215
	v_add_co_u32_e32 v16, vcc, s8, v10
	v_mul_f32_e32 v2, v18, v2
	v_mul_f32_e32 v3, v18, v3
	v_addc_co_u32_e32 v17, vcc, 0, v11, vcc
	v_mul_f32_e32 v4, v18, v4
	v_mul_f32_e32 v5, v18, v5
	v_cvt_pk_bf16_f32 v2, v2, v3
	v_cvt_pk_bf16_f32 v3, v4, v5
	global_store_dwordx2 v[14:15], v[2:3], off offset:3584
	s_nop 1
	v_mov_b32_e32 v2, v216
	v_mov_b32_e32 v3, v217
	v_mov_b32_e32 v4, v218
	v_mov_b32_e32 v5, v219
	v_add_co_u32_e32 v14, vcc, s1, v14
	v_mul_f32_e32 v2, v18, v2
	v_addc_co_u32_e32 v15, vcc, 0, v15, vcc
	v_mul_f32_e32 v3, v18, v3
	v_mul_f32_e32 v4, v18, v4
	v_mul_f32_e32 v5, v18, v5
	v_cvt_pk_bf16_f32 v2, v2, v3
	v_cvt_pk_bf16_f32 v3, v4, v5
	global_store_dwordx2 v[14:15], v[2:3], off
	s_nop 1
	v_mov_b32_e32 v2, v220
	v_mov_b32_e32 v3, v221
	v_mov_b32_e32 v4, v222
	v_mov_b32_e32 v5, v223
	v_add_co_u32_e32 v10, vcc, s9, v10
	v_mul_f32_e32 v2, v18, v2
	v_mul_f32_e32 v3, v18, v3
	v_mul_f32_e32 v4, v18, v4
	v_mul_f32_e32 v5, v18, v5
	v_cvt_pk_bf16_f32 v2, v2, v3
	v_cvt_pk_bf16_f32 v3, v4, v5
	global_store_dwordx2 v[14:15], v[2:3], off offset:512
	s_nop 1
	v_mov_b32_e32 v2, v224
	v_mov_b32_e32 v3, v225
	v_mov_b32_e32 v4, v226
	v_mov_b32_e32 v5, v227
	v_addc_co_u32_e32 v11, vcc, 0, v11, vcc
	v_mul_f32_e32 v2, v18, v2
	v_mul_f32_e32 v3, v18, v3
	v_mul_f32_e32 v4, v18, v4
	v_mul_f32_e32 v5, v18, v5
	v_cvt_pk_bf16_f32 v2, v2, v3
	v_cvt_pk_bf16_f32 v3, v4, v5
	global_store_dwordx2 v[14:15], v[2:3], off offset:1024
	s_nop 1
	v_mov_b32_e32 v2, v228
	v_mov_b32_e32 v3, v229
	v_mov_b32_e32 v4, v230
	v_mov_b32_e32 v5, v231
	v_mul_f32_e32 v2, v18, v2
	v_mul_f32_e32 v3, v18, v3
	v_mul_f32_e32 v4, v18, v4
	v_mul_f32_e32 v5, v18, v5
	v_cvt_pk_bf16_f32 v2, v2, v3
	v_cvt_pk_bf16_f32 v3, v4, v5
	global_store_dwordx2 v[14:15], v[2:3], off offset:1536
	s_nop 1
	v_mov_b32_e32 v2, v232
	v_mov_b32_e32 v3, v233
	v_mov_b32_e32 v4, v234
	v_mov_b32_e32 v5, v235
	v_mul_f32_e32 v2, v18, v2
	v_mul_f32_e32 v3, v18, v3
	v_mul_f32_e32 v4, v18, v4
	v_mul_f32_e32 v5, v18, v5
	v_cvt_pk_bf16_f32 v2, v2, v3
	v_cvt_pk_bf16_f32 v3, v4, v5
	global_store_dwordx2 v[14:15], v[2:3], off offset:2048
	s_nop 1
	v_mov_b32_e32 v2, v236
	v_mov_b32_e32 v3, v237
	v_mov_b32_e32 v4, v238
	v_mov_b32_e32 v5, v239
	v_mul_f32_e32 v2, v18, v2
	v_mul_f32_e32 v3, v18, v3
	v_mul_f32_e32 v4, v18, v4
	v_mul_f32_e32 v5, v18, v5
	v_cvt_pk_bf16_f32 v2, v2, v3
	v_cvt_pk_bf16_f32 v3, v4, v5
	global_store_dwordx2 v[14:15], v[2:3], off offset:2560
	s_nop 1
	v_mov_b32_e32 v2, v240
	v_mov_b32_e32 v3, v241
	v_mov_b32_e32 v4, v242
	v_mov_b32_e32 v5, v243
	v_mul_f32_e32 v2, v18, v2
	v_mul_f32_e32 v3, v18, v3
	v_mul_f32_e32 v4, v18, v4
	v_mul_f32_e32 v5, v18, v5
	v_cvt_pk_bf16_f32 v2, v2, v3
	v_cvt_pk_bf16_f32 v3, v4, v5
	global_store_dwordx2 v[14:15], v[2:3], off offset:3072
	s_nop 1
	v_mov_b32_e32 v2, v244
	v_mov_b32_e32 v3, v245
	v_mov_b32_e32 v4, v246
	v_mov_b32_e32 v5, v247
	v_mul_f32_e32 v2, v18, v2
	v_mul_f32_e32 v3, v18, v3
	v_mul_f32_e32 v4, v18, v4
	v_mul_f32_e32 v5, v18, v5
	v_cvt_pk_bf16_f32 v2, v2, v3
	v_cvt_pk_bf16_f32 v3, v4, v5
	global_store_dwordx2 v[14:15], v[2:3], off offset:3584
	flat_load_dwordx2 v[2:3], v[6:7] offset:64 sc0 sc1
	s_waitcnt vmcnt(0) lgkmcnt(0)
	v_lshl_add_u64 v[2:3], v[2:3], 0, s[6:7]
	flat_load_dword v20, v[2:3] offset:4
	s_nop 0
	flat_load_dwordx2 v[2:3], v[6:7] offset:80 sc0 sc1
	s_waitcnt vmcnt(0)
	s_or_b32 s6, s0, 1
	s_ashr_i32 s7, s6, 31
	s_lshl_b64 s[10:11], s[6:7], 14
	s_lshl_b64 s[6:7], s[6:7], 13
	s_waitcnt lgkmcnt(0)
	v_lshl_add_u64 v[2:3], v[2:3], 0, s[10:11]
	v_lshl_add_u64 v[6:7], v[2:3], 0, v[8:9]
	v_add_co_u32_e32 v212, vcc, 0x1000, v6
	s_nop 1
	v_addc_co_u32_e32 v213, vcc, 0, v7, vcc
	v_add_co_u32_e32 v228, vcc, 0x2000, v6
	s_nop 1
	v_addc_co_u32_e32 v229, vcc, 0, v7, vcc
	v_add_co_u32_e32 v244, vcc, 0x3000, v6
	s_nop 1
	v_addc_co_u32_e32 v245, vcc, 0, v7, vcc
	global_load_dwordx4 v[184:187], v[6:7], off nt
	global_load_dwordx4 v[188:191], v[6:7], off offset:1024 nt
	global_load_dwordx4 v[192:195], v[6:7], off offset:2048 nt
	global_load_dwordx4 v[196:199], v[6:7], off offset:3072 nt
	global_load_dwordx4 v[200:203], v[212:213], off nt
	global_load_dwordx4 v[204:207], v[212:213], off offset:1024 nt
	global_load_dwordx4 v[208:211], v[212:213], off offset:2048 nt
	global_load_dwordx4 v[212:215], v[212:213], off offset:3072 nt
	global_load_dwordx4 v[216:219], v[228:229], off nt
	global_load_dwordx4 v[220:223], v[228:229], off offset:1024 nt
	global_load_dwordx4 v[224:227], v[228:229], off offset:2048 nt
	global_load_dwordx4 v[228:231], v[228:229], off offset:3072 nt
	global_load_dwordx4 v[232:235], v[244:245], off nt
	global_load_dwordx4 v[236:239], v[244:245], off offset:1024 nt
	global_load_dwordx4 v[240:243], v[244:245], off offset:2048 nt
	global_load_dwordx4 v[244:247], v[244:245], off offset:3072 nt
	v_lshl_add_u64 v[8:9], v[12:13], 0, s[6:7]
	v_add_co_u32_e32 v10, vcc, s1, v6
	s_add_i32 s6, s26, s57
	s_nop 0
	v_addc_co_u32_e32 v11, vcc, 0, v7, vcc
	s_lshl_b32 s6, s6, 3
	s_mov_b64 s[10:11], 0x26000100
	s_movk_i32 s7, 0xffe0
	s_waitcnt vmcnt(0) lgkmcnt(0)
	v_mov_b32_e32 v2, v184
	v_mov_b32_e32 v3, v185
	v_mov_b32_e32 v4, v186
	v_mov_b32_e32 v5, v187
	v_mul_f32_e32 v2, v20, v2
	v_mul_f32_e32 v3, v20, v3
	v_mul_f32_e32 v4, v20, v4
	v_mul_f32_e32 v5, v20, v5
	v_cvt_pk_bf16_f32 v2, v2, v3
	v_cvt_pk_bf16_f32 v3, v4, v5
	global_store_dwordx2 v[8:9], v[2:3], off
	s_nop 1
	v_mov_b32_e32 v2, v188
	v_mov_b32_e32 v3, v189
	v_mov_b32_e32 v4, v190
	v_mov_b32_e32 v5, v191
	v_mul_f32_e32 v2, v20, v2
	v_mul_f32_e32 v3, v20, v3
	v_mul_f32_e32 v4, v20, v4
	v_mul_f32_e32 v5, v20, v5
	v_cvt_pk_bf16_f32 v2, v2, v3
	v_cvt_pk_bf16_f32 v3, v4, v5
	global_store_dwordx2 v[8:9], v[2:3], off offset:512
	s_nop 1
	v_mov_b32_e32 v2, v192
	v_mov_b32_e32 v3, v193
	v_mov_b32_e32 v4, v194
	v_mov_b32_e32 v5, v195
	v_mul_f32_e32 v2, v20, v2
	v_mul_f32_e32 v3, v20, v3
	v_mul_f32_e32 v4, v20, v4
	v_mul_f32_e32 v5, v20, v5
	v_cvt_pk_bf16_f32 v2, v2, v3
	v_cvt_pk_bf16_f32 v3, v4, v5
	global_store_dwordx2 v[8:9], v[2:3], off offset:1024
	s_nop 1
	v_mov_b32_e32 v2, v196
	v_mov_b32_e32 v3, v197
	v_mov_b32_e32 v4, v198
	v_mov_b32_e32 v5, v199
	v_mul_f32_e32 v2, v20, v2
	v_mul_f32_e32 v3, v20, v3
	v_mul_f32_e32 v4, v20, v4
	v_mul_f32_e32 v5, v20, v5
	v_cvt_pk_bf16_f32 v2, v2, v3
	v_cvt_pk_bf16_f32 v3, v4, v5
	global_store_dwordx2 v[8:9], v[2:3], off offset:1536
	s_nop 1
	v_mov_b32_e32 v2, v200
	v_mov_b32_e32 v3, v201
	v_mov_b32_e32 v4, v202
	v_mov_b32_e32 v5, v203
	v_mul_f32_e32 v2, v20, v2
	v_mul_f32_e32 v3, v20, v3
	v_mul_f32_e32 v4, v20, v4
	v_mul_f32_e32 v5, v20, v5
	v_cvt_pk_bf16_f32 v2, v2, v3
	v_cvt_pk_bf16_f32 v3, v4, v5
	global_store_dwordx2 v[8:9], v[2:3], off offset:2048
	s_nop 1
	v_mov_b32_e32 v2, v204
	v_mov_b32_e32 v3, v205
	v_mov_b32_e32 v4, v206
	v_mov_b32_e32 v5, v207
	v_mul_f32_e32 v2, v20, v2
	v_mul_f32_e32 v3, v20, v3
	v_mul_f32_e32 v4, v20, v4
	v_mul_f32_e32 v5, v20, v5
	v_cvt_pk_bf16_f32 v2, v2, v3
	v_cvt_pk_bf16_f32 v3, v4, v5
	global_store_dwordx2 v[8:9], v[2:3], off offset:2560
	s_nop 1
	v_mov_b32_e32 v2, v208
	v_mov_b32_e32 v3, v209
	v_mov_b32_e32 v4, v210
	v_mov_b32_e32 v5, v211
	v_mul_f32_e32 v2, v20, v2
	v_mul_f32_e32 v3, v20, v3
	v_mul_f32_e32 v4, v20, v4
	v_mul_f32_e32 v5, v20, v5
	v_cvt_pk_bf16_f32 v2, v2, v3
	v_cvt_pk_bf16_f32 v3, v4, v5
	global_store_dwordx2 v[8:9], v[2:3], off offset:3072
	s_nop 1
	v_mov_b32_e32 v2, v212
	v_mov_b32_e32 v3, v213
	v_mov_b32_e32 v4, v214
	v_mov_b32_e32 v5, v215
	v_add_co_u32_e32 v10, vcc, s8, v6
	v_mul_f32_e32 v2, v20, v2
	v_mul_f32_e32 v3, v20, v3
	v_addc_co_u32_e32 v11, vcc, 0, v7, vcc
	v_mul_f32_e32 v4, v20, v4
	v_mul_f32_e32 v5, v20, v5
	v_cvt_pk_bf16_f32 v2, v2, v3
	v_cvt_pk_bf16_f32 v3, v4, v5
	global_store_dwordx2 v[8:9], v[2:3], off offset:3584
	s_nop 1
	v_mov_b32_e32 v2, v216
	v_mov_b32_e32 v3, v217
	v_mov_b32_e32 v4, v218
	v_mov_b32_e32 v5, v219
	v_add_co_u32_e32 v16, vcc, s1, v8
	v_lshlrev_b32_e32 v8, 3, v150
	s_nop 0
	v_addc_co_u32_e32 v17, vcc, 0, v9, vcc
	v_add_co_u32_e32 v6, vcc, s9, v6
	v_ashrrev_i32_e32 v9, 31, v8
	s_nop 0
	v_addc_co_u32_e32 v7, vcc, 0, v7, vcc
	v_lshlrev_b64 v[18:19], 1, v[8:9]
	s_mov_b64 s[8:9], 0x4e500100
	s_mov_b64 s[0:1], 0x200
	v_mul_f32_e32 v2, v20, v2
	v_mul_f32_e32 v3, v20, v3
	v_mul_f32_e32 v4, v20, v4
	v_mul_f32_e32 v5, v20, v5
	v_cvt_pk_bf16_f32 v2, v2, v3
	v_cvt_pk_bf16_f32 v3, v4, v5
	global_store_dwordx2 v[16:17], v[2:3], off
	s_nop 1
	v_mov_b32_e32 v2, v220
	v_mov_b32_e32 v3, v221
	v_mov_b32_e32 v4, v222
	v_mov_b32_e32 v5, v223
	v_mul_f32_e32 v2, v20, v2
	v_mul_f32_e32 v3, v20, v3
	v_mul_f32_e32 v4, v20, v4
	v_mul_f32_e32 v5, v20, v5
	v_cvt_pk_bf16_f32 v2, v2, v3
	v_cvt_pk_bf16_f32 v3, v4, v5
	global_store_dwordx2 v[16:17], v[2:3], off offset:512
	s_nop 1
	v_mov_b32_e32 v2, v224
	v_mov_b32_e32 v3, v225
	v_mov_b32_e32 v4, v226
	v_mov_b32_e32 v5, v227
	v_mul_f32_e32 v2, v20, v2
	v_mul_f32_e32 v3, v20, v3
	v_mul_f32_e32 v4, v20, v4
	v_mul_f32_e32 v5, v20, v5
	v_cvt_pk_bf16_f32 v2, v2, v3
	v_cvt_pk_bf16_f32 v3, v4, v5
	global_store_dwordx2 v[16:17], v[2:3], off offset:1024
	s_nop 1
	v_mov_b32_e32 v2, v228
	v_mov_b32_e32 v3, v229
	v_mov_b32_e32 v4, v230
	v_mov_b32_e32 v5, v231
	v_bfi_b32 v10, -16, s6, v134
	v_ashrrev_i32_e32 v11, 31, v10
	v_lshlrev_b64 v[10:11], 13, v[10:11]
	v_or_b32_e32 v10, s12, v10
	v_lshl_add_u64 v[10:11], v[10:11], 0, v[18:19]
	v_lshl_add_u64 v[10:11], s[78:79], 0, v[10:11]
	v_lshl_add_u64 v[10:11], v[10:11], 0, s[10:11]
	v_mul_f32_e32 v2, v20, v2
	v_mul_f32_e32 v3, v20, v3
	v_mul_f32_e32 v4, v20, v4
	v_mul_f32_e32 v5, v20, v5
	v_cvt_pk_bf16_f32 v2, v2, v3
	v_cvt_pk_bf16_f32 v3, v4, v5
	global_store_dwordx2 v[16:17], v[2:3], off offset:1536
	s_nop 1
	v_mov_b32_e32 v2, v232
	v_mov_b32_e32 v3, v233
	v_mov_b32_e32 v4, v234
	v_mov_b32_e32 v5, v235
	v_mul_f32_e32 v2, v20, v2
	v_mul_f32_e32 v3, v20, v3
	v_mul_f32_e32 v4, v20, v4
	v_mul_f32_e32 v5, v20, v5
	v_cvt_pk_bf16_f32 v2, v2, v3
	v_cvt_pk_bf16_f32 v3, v4, v5
	global_store_dwordx2 v[16:17], v[2:3], off offset:2048
	s_nop 1
	v_mov_b32_e32 v2, v236
	v_mov_b32_e32 v3, v237
	v_mov_b32_e32 v4, v238
	v_mov_b32_e32 v5, v239
	v_mul_f32_e32 v2, v20, v2
	v_mul_f32_e32 v3, v20, v3
	v_mul_f32_e32 v4, v20, v4
	v_mul_f32_e32 v5, v20, v5
	v_cvt_pk_bf16_f32 v2, v2, v3
	v_cvt_pk_bf16_f32 v3, v4, v5
	global_store_dwordx2 v[16:17], v[2:3], off offset:2560
	s_nop 1
	v_mov_b32_e32 v2, v240
	v_mov_b32_e32 v3, v241
	v_mov_b32_e32 v4, v242
	v_mov_b32_e32 v5, v243
	v_mul_f32_e32 v2, v20, v2
	v_mul_f32_e32 v3, v20, v3
	v_mul_f32_e32 v4, v20, v4
	v_mul_f32_e32 v5, v20, v5
	v_cvt_pk_bf16_f32 v2, v2, v3
	v_cvt_pk_bf16_f32 v3, v4, v5
	global_store_dwordx2 v[16:17], v[2:3], off offset:3072
	s_nop 1
	v_mov_b32_e32 v12, v244
	v_mov_b32_e32 v13, v245
	v_mov_b32_e32 v14, v246
	v_mov_b32_e32 v15, v247
	v_and_b32_e32 v6, 15, v134
	v_mov_b32_e32 v3, 0
	v_lshl_or_b32 v2, v6, 13, s12
	v_lshl_add_u64 v[8:9], v[2:3], 0, v[18:19]
	v_lshl_add_u64 v[8:9], s[78:79], 0, v[8:9]
	v_mov_b32_e32 v4, v3
	v_mov_b32_e32 v2, v3
	v_lshl_add_u64 v[8:9], v[8:9], 0, s[8:9]
	v_mul_f32_e32 v5, v20, v12
	v_mul_f32_e32 v7, v20, v13
	v_mul_f32_e32 v13, v20, v14
	v_cvt_pk_bf16_f32 v12, v5, v7
	v_mov_b32_e32 v5, v3
	v_mul_f32_e32 v14, v20, v15
	v_cvt_pk_bf16_f32 v13, v13, v14
	global_store_dwordx2 v[16:17], v[12:13], off offset:3584
